# E4c + MLA loop head: the DMA-issue code of waves 4-7 moved out of line so waves 0-3 fall through into their first K-fragment reads
# baseline (speedup 1.0000x reference)
.Lmla_dma1:
	s_lshl_b64 s[14:15], s[50:51], 13
	s_add_u32 s44, s80, s14
	s_addc_u32 s45, s81, s15
	s_add_u32 s14, s78, s14
	s_addc_u32 s15, s79, s15
	s_cmp_lg_u32 0, -1
	s_cselect_b32 s16, 0, 0
	s_add_i32 s16, s16, s41
	v_lshl_add_u64 v[80:81], s[44:45], 0, v[128:129]
	s_add_i32 s23, s16, 0x4000
	s_mov_b32 m0, s23
	s_nop 0
	global_load_lds_dwordx4 v[80:81], off
	v_lshl_add_u64 v[80:81], s[44:45], 0, v[192:193]
	s_add_i32 s23, s16, 0x6000
	s_mov_b32 m0, s23
	s_nop 0
	global_load_lds_dwordx4 v[80:81], off
	v_lshl_add_u64 v[80:81], s[14:15], 0, v[190:191]
	s_add_i32 s23, s16, 0xc000
	s_mov_b32 m0, s23
	s_nop 0
	global_load_lds_dwordx4 v[80:81], off
	v_lshl_add_u64 v[80:81], s[14:15], 0, v[188:189]
	s_add_i32 s14, s16, 0xe000
	s_mov_b32 m0, s14
	s_nop 0
	global_load_lds_dwordx4 v[80:81], off
	s_lshl_b64 s[14:15], s[50:51], 7
	v_lshl_add_u64 v[80:81], v[194:195], 0, s[14:15]
	s_add_i32 s16, s16, 0x12800
	s_mov_b32 m0, s16
	s_nop 0
	global_load_lds_dwordx4 v[80:81], off
	s_lshl_b64 s[14:15], s[50:51], 13
	s_add_u32 s44, s80, s14
	s_addc_u32 s45, s81, s15
	s_add_u32 s14, s78, s14
	s_addc_u32 s15, s79, s15
	s_sub_u32 s44, s44, 0x20000
	s_subb_u32 s45, s45, 0
	s_sub_u32 s14, s14, 0x20000
	s_subb_u32 s15, s15, 0
	s_add_i32 s16, s41, 0xfffff000
	v_lshl_add_u64 v[80:81], s[44:45], 0, v[128:129]
	s_add_i32 s23, s16, 0x4000
	s_mov_b32 m0, s23
	s_nop 0
	global_load_lds_dwordx4 v[80:81], off
	v_lshl_add_u64 v[80:81], s[44:45], 0, v[192:193]
	s_add_i32 s23, s16, 0x6000
	s_mov_b32 m0, s23
	s_nop 0
	global_load_lds_dwordx4 v[80:81], off
	v_lshl_add_u64 v[80:81], s[14:15], 0, v[190:191]
	s_add_i32 s23, s16, 0xc000
	s_mov_b32 m0, s23
	s_nop 0
	global_load_lds_dwordx4 v[80:81], off
	v_lshl_add_u64 v[80:81], s[14:15], 0, v[188:189]
	s_add_i32 s23, s16, 0xe000
	s_mov_b32 m0, s23
	s_nop 0
	global_load_lds_dwordx4 v[80:81], off
	s_lshl_b64 s[14:15], s[50:51], 7
	s_sub_u32 s14, s14, 0x1000
	s_subb_u32 s15, s15, 0
	v_lshl_add_u64 v[80:81], v[194:195], 0, s[14:15]
	s_add_i32 s23, s16, 0x12800
	s_mov_b32 m0, s23
	s_nop 0
	global_load_lds_dwordx4 v[80:81], off
	s_branch .Lmla_dma1_ret
.Lmla_dma2:
	s_mov_b32 s83, s51
	s_lshl_b64 s[14:15], s[82:83], 13
	s_add_u32 s44, s80, s14
	s_addc_u32 s45, s81, s15
	s_add_u32 s14, s78, s14
	s_addc_u32 s15, s79, s15
	v_lshl_add_u64 v[96:97], s[44:45], 0, v[128:129]
	s_mov_b32 m0, s97
	s_nop 0
	global_load_lds_dwordx4 v[96:97], off
	s_cmp_lg_u32 0, -1
	s_cselect_b32 s16, 0, 0
	s_add_i32 s16, s16, s41
	v_lshl_add_u64 v[96:97], s[44:45], 0, v[192:193]
	s_add_i32 s23, s16, 0x2000
	s_mov_b32 m0, s23
	s_nop 0
	global_load_lds_dwordx4 v[96:97], off
	v_lshl_add_u64 v[96:97], s[14:15], 0, v[190:191]
	s_mov_b32 m0, s40
	s_nop 0
	global_load_lds_dwordx4 v[96:97], off
	v_lshl_add_u64 v[96:97], s[14:15], 0, v[188:189]
	s_add_i32 s16, s16, 0xa000
	s_mov_b32 m0, s16
	s_nop 0
	global_load_lds_dwordx4 v[96:97], off
	s_lshl_b64 s[14:15], s[82:83], 7
	v_lshl_add_u64 v[96:97], v[194:195], 0, s[14:15]
	s_mov_b32 m0, s46
	s_nop 0
	global_load_lds_dwordx4 v[96:97], off
	s_lshl_b64 s[14:15], s[82:83], 13
	s_add_u32 s44, s80, s14
	s_addc_u32 s45, s81, s15
	s_add_u32 s14, s78, s14
	s_addc_u32 s15, s79, s15
	s_sub_u32 s44, s44, 0x20000
	s_subb_u32 s45, s45, 0
	s_sub_u32 s14, s14, 0x20000
	s_subb_u32 s15, s15, 0
	s_add_i32 s16, s41, 0xfffff000
	v_lshl_add_u64 v[96:97], s[44:45], 0, v[128:129]
	s_add_i32 s23, s97, 0xfffff000
	s_mov_b32 m0, s23
	s_nop 0
	global_load_lds_dwordx4 v[96:97], off
	v_lshl_add_u64 v[96:97], s[44:45], 0, v[192:193]
	s_add_i32 s23, s16, 0x2000
	s_mov_b32 m0, s23
	s_nop 0
	global_load_lds_dwordx4 v[96:97], off
	v_lshl_add_u64 v[96:97], s[14:15], 0, v[190:191]
	s_add_i32 s23, s40, 0xfffff000
	s_mov_b32 m0, s23
	s_nop 0
	global_load_lds_dwordx4 v[96:97], off
	v_lshl_add_u64 v[96:97], s[14:15], 0, v[188:189]
	s_add_i32 s23, s16, 0xa000
	s_mov_b32 m0, s23
	s_nop 0
	global_load_lds_dwordx4 v[96:97], off
	s_lshl_b64 s[14:15], s[82:83], 7
	s_sub_u32 s14, s14, 0x1000
	s_subb_u32 s15, s15, 0
	v_lshl_add_u64 v[96:97], v[194:195], 0, s[14:15]
	s_add_i32 s23, s46, 0xfffff000
	s_mov_b32 m0, s23
	s_nop 0
	global_load_lds_dwordx4 v[96:97], off
	s_branch .LBB0_844

.LBB0_828:
	s_sub_i32 s50, s82, 64
	s_cmp_ge_u32 s3, 0x100
	s_cbranch_scc1 .Lmla_dma1

.LBB0_842:
	v_exp_f32_e32 v178, v112
	v_exp_f32_e32 v179, v113
	v_exp_f32_e32 v114, v114
	v_exp_f32_e32 v115, v115
	v_exp_f32_e32 v116, v116
	v_exp_f32_e32 v180, v96
	v_add_f32_e32 v96, 0, v178
	v_exp_f32_e32 v117, v117
	v_add_f32_e32 v96, v179, v96
	v_exp_f32_e32 v118, v118
	v_add_f32_e32 v96, v114, v96
	v_exp_f32_e32 v119, v119
	v_add_f32_e32 v96, v115, v96
	v_exp_f32_e32 v120, v120
	v_add_f32_e32 v96, v116, v96
	v_exp_f32_e32 v121, v121
	v_add_f32_e32 v96, v117, v96
	v_exp_f32_e32 v122, v122
	v_add_f32_e32 v96, v118, v96
	v_exp_f32_e32 v123, v123
	v_add_f32_e32 v96, v119, v96
	v_exp_f32_e32 v124, v124
	v_add_f32_e32 v96, v120, v96
	v_exp_f32_e32 v125, v125
	v_add_f32_e32 v96, v121, v96
	v_exp_f32_e32 v126, v126
	v_add_f32_e32 v96, v122, v96
	v_exp_f32_e32 v127, v127
	v_add_f32_e32 v96, v123, v96
	v_add_f32_e32 v96, v124, v96
	v_exp_f32_e32 v181, v97
	v_add_f32_e32 v96, v125, v96
	v_exp_f32_e32 v232, v98
	v_add_f32_e32 v96, v126, v96
	v_exp_f32_e32 v233, v99
	v_add_f32_e32 v96, v127, v96
	v_exp_f32_e32 v234, v100
	v_add_f32_e32 v96, v180, v96
	v_exp_f32_e32 v235, v101
	v_add_f32_e32 v96, v181, v96
	v_exp_f32_e32 v236, v102
	v_add_f32_e32 v96, v232, v96
	v_exp_f32_e32 v237, v103
	v_add_f32_e32 v96, v233, v96
	v_exp_f32_e32 v238, v104
	v_add_f32_e32 v96, v234, v96
	v_exp_f32_e32 v239, v105
	v_add_f32_e32 v96, v235, v96
	v_exp_f32_e32 v240, v106
	v_add_f32_e32 v96, v236, v96
	v_exp_f32_e32 v241, v107
	v_add_f32_e32 v96, v237, v96
	v_exp_f32_e32 v242, v108
	v_add_f32_e32 v96, v238, v96
	v_exp_f32_e32 v243, v109
	v_add_f32_e32 v96, v239, v96
	v_exp_f32_e32 v244, v110
	v_add_f32_e32 v96, v240, v96
	v_exp_f32_e32 v111, v111
	v_add_f32_e32 v96, v241, v96
	v_add_f32_e32 v96, v242, v96
	v_add_f32_e32 v96, v243, v96
	v_add_f32_e32 v96, v244, v96
	v_add_f32_e32 v112, v111, v96
	v_mov_b32_e32 v113, v112
	s_nop 1
	v_permlane32_swap_b32_e32 v112, v113
	v_cvt_pk_bf16_f32 v96, v178, v179
	v_cvt_pk_bf16_f32 v97, v114, v115
	v_cvt_pk_bf16_f32 v98, v116, v117
	v_cvt_pk_bf16_f32 v99, v118, v119
	v_cvt_pk_bf16_f32 v100, v120, v121
	v_cvt_pk_bf16_f32 v101, v122, v123
	v_cvt_pk_bf16_f32 v102, v124, v125
	v_cvt_pk_bf16_f32 v103, v126, v127
	v_cvt_pk_bf16_f32 v104, v180, v181
	v_cvt_pk_bf16_f32 v105, v232, v233
	v_cvt_pk_bf16_f32 v106, v234, v235
	v_cvt_pk_bf16_f32 v107, v236, v237
	v_cvt_pk_bf16_f32 v108, v238, v239
	v_cvt_pk_bf16_f32 v109, v240, v241
	v_cvt_pk_bf16_f32 v110, v242, v243
	v_cvt_pk_bf16_f32 v111, v244, v111
	s_nop 0
	v_permlane32_swap_b32_e32 v96, v98
	v_permlane32_swap_b32_e32 v97, v99
	v_permlane32_swap_b32_e32 v100, v102
	v_permlane32_swap_b32_e32 v101, v103
	v_permlane32_swap_b32_e32 v104, v106
	v_permlane32_swap_b32_e32 v105, v107
	v_permlane32_swap_b32_e32 v108, v110
	v_permlane32_swap_b32_e32 v109, v111
	ds_read_b64_tr_b16 v[114:115], v185 offset:0
	ds_read_b64_tr_b16 v[116:117], v185 offset:0x800
	ds_read_b64_tr_b16 v[118:119], v185 offset:0x1000
	ds_read_b64_tr_b16 v[120:121], v185 offset:0x1800
	ds_read_b64_tr_b16 v[122:123], v185 offset:0x2000
	ds_read_b64_tr_b16 v[124:125], v185 offset:0x2800
	ds_read_b64_tr_b16 v[232:233], v185 offset:0x3000
	ds_read_b64_tr_b16 v[234:235], v185 offset:0x3800
	ds_read_b64_tr_b16 v[236:237], v185 offset:0x200
	ds_read_b64_tr_b16 v[238:239], v185 offset:0xa00
	ds_read_b64_tr_b16 v[240:241], v185 offset:0x1200
	ds_read_b64_tr_b16 v[242:243], v185 offset:0x1a00
	ds_read_b64_tr_b16 v[244:245], v185 offset:0x2200
	ds_read_b64_tr_b16 v[246:247], v185 offset:0x2a00
	ds_read_b64_tr_b16 v[248:249], v185 offset:0x3200
	ds_read_b64_tr_b16 v[250:251], v185 offset:0x3a00
	s_waitcnt lgkmcnt(8)
	s_setprio 1
	v_mfma_f32_32x32x16_bf16 v[16:31], v[96:99], v[114:117], v[16:31]
	v_mfma_f32_32x32x16_bf16 v[16:31], v[100:103], v[118:121], v[16:31]
	v_mfma_f32_32x32x16_bf16 v[16:31], v[104:107], v[122:125], v[16:31]
	v_mfma_f32_32x32x16_bf16 v[16:31], v[108:111], v[232:235], v[16:31]
	s_setprio 0
	ds_read_b64_tr_b16 v[114:115], v185 offset:0x400
	ds_read_b64_tr_b16 v[116:117], v185 offset:0xc00
	ds_read_b64_tr_b16 v[118:119], v185 offset:0x1400
	ds_read_b64_tr_b16 v[120:121], v185 offset:0x1c00
	ds_read_b64_tr_b16 v[122:123], v185 offset:0x2400
	ds_read_b64_tr_b16 v[124:125], v185 offset:0x2c00
	ds_read_b64_tr_b16 v[232:233], v185 offset:0x3400
	ds_read_b64_tr_b16 v[234:235], v185 offset:0x3c00
	s_waitcnt lgkmcnt(8)
	s_setprio 1
	v_mfma_f32_32x32x16_bf16 v[48:63], v[96:99], v[236:239], v[48:63]
	v_mfma_f32_32x32x16_bf16 v[48:63], v[100:103], v[240:243], v[48:63]
	v_mfma_f32_32x32x16_bf16 v[48:63], v[104:107], v[244:247], v[48:63]
	v_mfma_f32_32x32x16_bf16 v[48:63], v[108:111], v[248:251], v[48:63]
	s_setprio 0
	ds_read_b64_tr_b16 v[236:237], v185 offset:0x600
	ds_read_b64_tr_b16 v[238:239], v185 offset:0xe00
	ds_read_b64_tr_b16 v[240:241], v185 offset:0x1600
	ds_read_b64_tr_b16 v[242:243], v185 offset:0x1e00
	ds_read_b64_tr_b16 v[244:245], v185 offset:0x2600
	ds_read_b64_tr_b16 v[246:247], v185 offset:0x2e00
	ds_read_b64_tr_b16 v[248:249], v185 offset:0x3600
	ds_read_b64_tr_b16 v[250:251], v185 offset:0x3e00
	s_waitcnt lgkmcnt(8)
	s_setprio 1
	v_mfma_f32_32x32x16_bf16 v[32:47], v[96:99], v[114:117], v[32:47]
	v_mfma_f32_32x32x16_bf16 v[32:47], v[100:103], v[118:121], v[32:47]
	v_mfma_f32_32x32x16_bf16 v[32:47], v[104:107], v[122:125], v[32:47]
	v_mfma_f32_32x32x16_bf16 v[32:47], v[108:111], v[232:235], v[32:47]
	s_setprio 0
	s_waitcnt lgkmcnt(0)
	s_setprio 1
	v_mfma_f32_32x32x16_bf16 v[0:15], v[96:99], v[236:239], v[0:15]
	v_mfma_f32_32x32x16_bf16 v[0:15], v[100:103], v[240:243], v[0:15]
	v_mfma_f32_32x32x16_bf16 v[0:15], v[104:107], v[244:247], v[0:15]
	v_mfma_f32_32x32x16_bf16 v[0:15], v[108:111], v[248:251], v[0:15]
	s_setprio 0
	s_waitcnt vmcnt(0)
	s_add_i32 s5, s5, 2
	s_cmp_ge_i32 s5, s13
	s_barrier
	s_cbranch_scc1 .LBB0_844
	s_cmp_ge_u32 s3, 0x100
	s_cbranch_scc1 .Lmla_dma2
